# phase-3 output-gate loads issued at start of the MFMA section
# speedup vs baseline: 1.0167x; 1.0110x over previous
.LBB0_422:
	s_or_b64 exec, exec, s[36:37]
	s_waitcnt lgkmcnt(0)
	s_barrier
	v_mov_b32_e32 v232, v156
	v_ashrrev_i32_e32 v233, 31, v156
	v_lshl_add_u64 v[232:233], v[232:233], 0, s[46:47]
	v_lshlrev_b64 v[232:233], 8, v[232:233]
	v_lshl_add_u64 v[232:233], v[150:151], 0, v[232:233]
	global_load_dwordx4 v[216:219], v[232:233], off offset:48
	global_load_dwordx4 v[220:223], v[232:233], off offset:32
	global_load_dwordx4 v[224:227], v[232:233], off offset:16
	global_load_dwordx4 v[228:231], v[232:233], off
	ds_read_b128 v[0:3], v167
	ds_read_b128 v[4:7], v167 offset:416
	ds_read_b128 v[8:11], v167 offset:448
	v_add_u32_e32 v157, v170, v179
	s_add_u32 s52, s52, 0x4000
	s_waitcnt lgkmcnt(2)
	v_pk_mul_f32 v[48:49], v[108:109], v[0:1]
	v_pk_mul_f32 v[50:51], v[114:115], v[2:3]
	ds_read_b128 v[0:3], v167 offset:32
	ds_read_b128 v[12:15], v167 offset:480
	v_cvt_pk_bf16_f32 v64, v48, v49
	v_cvt_pk_bf16_f32 v65, v50, v51
	s_waitcnt lgkmcnt(3)
	v_pk_mul_f32 v[4:5], v[144:145], v[4:5]
	s_waitcnt lgkmcnt(1)
	v_pk_mul_f32 v[52:53], v[52:53], v[0:1]
	v_pk_mul_f32 v[54:55], v[54:55], v[2:3]
	ds_read_b128 v[0:3], v167 offset:64
	v_cvt_pk_bf16_f32 v66, v52, v53
	v_cvt_pk_bf16_f32 v67, v54, v55
	v_pk_mul_f32 v[6:7], v[138:139], v[6:7]
	v_pk_mul_f32 v[8:9], v[146:147], v[8:9]
	s_waitcnt lgkmcnt(0)
	v_pk_mul_f32 v[56:57], v[56:57], v[0:1]
	v_pk_mul_f32 v[58:59], v[58:59], v[2:3]
	ds_read_b128 v[0:3], v167 offset:96
	v_pk_mul_f32 v[10:11], v[140:141], v[10:11]
	v_pk_mul_f32 v[12:13], v[148:149], v[12:13]
	v_pk_mul_f32 v[14:15], v[142:143], v[14:15]
	s_addc_u32 s53, s53, 0
	s_waitcnt lgkmcnt(0)
	v_pk_mul_f32 v[60:61], v[60:61], v[0:1]
	v_pk_mul_f32 v[62:63], v[62:63], v[2:3]
	ds_read_b128 v[0:3], v167 offset:128
	s_cmp_eq_u32 s52, 0x20000
	s_waitcnt lgkmcnt(0)
	v_pk_mul_f32 v[32:33], v[100:101], v[0:1]
	v_pk_mul_f32 v[34:35], v[96:97], v[2:3]
	ds_read_b128 v[0:3], v167 offset:160
	v_cvt_pk_bf16_f32 v100, v56, v57
	v_cvt_pk_bf16_f32 v101, v58, v59
	s_waitcnt lgkmcnt(0)
	v_pk_mul_f32 v[36:37], v[110:111], v[0:1]
	v_pk_mul_f32 v[38:39], v[102:103], v[2:3]
	ds_read_b128 v[0:3], v167 offset:192
	v_cvt_pk_bf16_f32 v102, v60, v61
	v_cvt_pk_bf16_f32 v103, v62, v63
	s_waitcnt lgkmcnt(0)
	v_pk_mul_f32 v[40:41], v[104:105], v[0:1]
	v_pk_mul_f32 v[42:43], v[98:99], v[2:3]
	ds_read_b128 v[0:3], v167 offset:224
	v_add_u32_e32 v104, 0x2000, v180
	s_waitcnt lgkmcnt(0)
	v_pk_mul_f32 v[44:45], v[116:117], v[0:1]
	v_pk_mul_f32 v[46:47], v[106:107], v[2:3]
	ds_read_b128 v[0:3], v167 offset:256
	s_waitcnt lgkmcnt(0)
	v_pk_mul_f32 v[16:17], v[122:123], v[0:1]
	v_pk_mul_f32 v[18:19], v[118:119], v[2:3]
	ds_read_b128 v[0:3], v167 offset:288
	s_waitcnt lgkmcnt(0)
	v_pk_mul_f32 v[20:21], v[130:131], v[0:1]
	v_pk_mul_f32 v[22:23], v[124:125], v[2:3]
	ds_read_b128 v[0:3], v167 offset:320
	s_waitcnt lgkmcnt(0)
	v_pk_mul_f32 v[24:25], v[126:127], v[0:1]
	v_pk_mul_f32 v[26:27], v[120:121], v[2:3]
	ds_read_b128 v[0:3], v167 offset:352
	s_waitcnt lgkmcnt(0)
	v_pk_mul_f32 v[28:29], v[132:133], v[0:1]
	v_pk_mul_f32 v[30:31], v[128:129], v[2:3]
	ds_read_b128 v[0:3], v167 offset:384
	ds_read2_b64 v[68:71], v180 offset1:2
	ds_read2_b64 v[96:99], v180 offset0:4 offset1:6
	s_waitcnt lgkmcnt(1)
	v_mfma_f32_32x32x16_bf16 v[80:95], v[64:67], v[68:71], 0
	ds_read2_b64 v[68:71], v104 offset0:64 offset1:66
	v_mul_f32_e64 v0, v136, v0
	v_mul_f32_e64 v1, v137, v1
	v_mul_f32_e64 v2, v134, v2
	v_mul_f32_e64 v3, v135, v3
	s_waitcnt lgkmcnt(0)
	v_mfma_f32_32x32x16_bf16 v[64:79], v[64:67], v[68:71], 0
	v_mfma_f32_32x32x16_bf16 v[80:95], v[100:103], v[96:99], v[80:95]
	ds_read2_b64 v[96:99], v104 offset0:68 offset1:70
	s_waitcnt lgkmcnt(0)
	v_mfma_f32_32x32x16_bf16 v[64:79], v[100:103], v[96:99], v[64:79]
	v_cvt_pk_bf16_f32 v96, v32, v33
	v_cvt_pk_bf16_f32 v97, v34, v35
	v_cvt_pk_bf16_f32 v98, v36, v37
	v_cvt_pk_bf16_f32 v99, v38, v39
	ds_read2_b64 v[100:103], v180 offset0:8 offset1:10
	s_waitcnt lgkmcnt(0)
	v_mfma_f32_32x32x16_bf16 v[80:95], v[96:99], v[100:103], v[80:95]
	ds_read2_b64 v[100:103], v104 offset0:72 offset1:74
	s_waitcnt lgkmcnt(0)
	v_mfma_f32_32x32x16_bf16 v[64:79], v[96:99], v[100:103], v[64:79]
	v_cvt_pk_bf16_f32 v96, v40, v41
	v_cvt_pk_bf16_f32 v97, v42, v43
	v_cvt_pk_bf16_f32 v98, v44, v45
	v_cvt_pk_bf16_f32 v99, v46, v47
	ds_read2_b64 v[100:103], v180 offset0:12 offset1:14
	s_waitcnt lgkmcnt(0)
	v_mfma_f32_32x32x16_bf16 v[80:95], v[96:99], v[100:103], v[80:95]
	ds_read2_b64 v[100:103], v104 offset0:76 offset1:78
	s_waitcnt lgkmcnt(0)
	v_mfma_f32_32x32x16_bf16 v[64:79], v[96:99], v[100:103], v[64:79]
	v_cvt_pk_bf16_f32 v96, v16, v17
	v_cvt_pk_bf16_f32 v97, v18, v19
	v_cvt_pk_bf16_f32 v98, v20, v21
	v_cvt_pk_bf16_f32 v99, v22, v23
	ds_read2_b64 v[100:103], v180 offset0:16 offset1:18
	s_waitcnt lgkmcnt(0)
	v_mfma_f32_32x32x16_bf16 v[80:95], v[96:99], v[100:103], v[80:95]
	ds_read2_b64 v[100:103], v104 offset0:80 offset1:82
	s_waitcnt lgkmcnt(0)
	v_mfma_f32_32x32x16_bf16 v[64:79], v[96:99], v[100:103], v[64:79]
	v_cvt_pk_bf16_f32 v96, v24, v25
	v_cvt_pk_bf16_f32 v97, v26, v27
	v_cvt_pk_bf16_f32 v98, v28, v29
	v_cvt_pk_bf16_f32 v99, v30, v31
	ds_read2_b64 v[100:103], v180 offset0:20 offset1:22
	s_waitcnt lgkmcnt(0)
	v_mfma_f32_32x32x16_bf16 v[80:95], v[96:99], v[100:103], v[80:95]
	ds_read2_b64 v[100:103], v104 offset0:84 offset1:86
	s_waitcnt lgkmcnt(0)
	v_mfma_f32_32x32x16_bf16 v[64:79], v[96:99], v[100:103], v[64:79]
	v_cvt_pk_bf16_f32 v96, v0, v1
	v_cvt_pk_bf16_f32 v97, v2, v3
	v_cvt_pk_bf16_f32 v98, v4, v5
	v_cvt_pk_bf16_f32 v99, v6, v7
	ds_read2_b64 v[100:103], v180 offset0:24 offset1:26
	s_waitcnt lgkmcnt(0)
	v_mfma_f32_32x32x16_bf16 v[80:95], v[96:99], v[100:103], v[80:95]
	ds_read2_b64 v[100:103], v104 offset0:88 offset1:90
	s_waitcnt lgkmcnt(0)
	v_mfma_f32_32x32x16_bf16 v[64:79], v[96:99], v[100:103], v[64:79]
	v_cvt_pk_bf16_f32 v96, v8, v9
	v_cvt_pk_bf16_f32 v97, v10, v11
	v_cvt_pk_bf16_f32 v98, v12, v13
	v_cvt_pk_bf16_f32 v99, v14, v15
	ds_read2_b64 v[100:103], v180 offset0:28 offset1:30
	s_waitcnt lgkmcnt(0)
	v_mfma_f32_32x32x16_bf16 v[80:95], v[96:99], v[100:103], v[80:95]
	ds_read2_b64 v[100:103], v104 offset0:92 offset1:94
	s_waitcnt lgkmcnt(0)
	v_mfma_f32_32x32x16_bf16 v[64:79], v[96:99], v[100:103], v[64:79]
	ds_read_b128 v[114:117], v157 offset:17408
	ds_read_b128 v[96:99], v157
	ds_read_b128 v[118:121], v157 offset:32
	ds_read_b128 v[122:125], v157 offset:17440
	s_waitcnt lgkmcnt(2)
	v_mfma_f32_32x32x16_bf16 v[96:111], v[114:117], v[96:99], 0
	s_waitcnt lgkmcnt(0)
	v_mfma_f32_32x32x16_bf16 v[96:111], v[122:125], v[118:121], v[96:111]
	ds_read_b128 v[118:121], v157 offset:17472
	ds_read_b128 v[126:129], v157 offset:64
	s_waitcnt lgkmcnt(0)
	v_mfma_f32_32x32x16_bf16 v[96:111], v[118:121], v[126:129], v[96:111]
	ds_read_b128 v[126:129], v157 offset:17504
	ds_read_b128 v[130:133], v157 offset:96
	s_waitcnt lgkmcnt(0)
	v_mfma_f32_32x32x16_bf16 v[96:111], v[126:129], v[130:133], v[96:111]
	ds_read_b128 v[130:133], v157 offset:17536
	ds_read_b128 v[134:137], v157 offset:128
	s_waitcnt lgkmcnt(0)
	v_mfma_f32_32x32x16_bf16 v[96:111], v[130:133], v[134:137], v[96:111]
	ds_read_b128 v[134:137], v157 offset:17568
	ds_read_b128 v[138:141], v157 offset:160
	s_waitcnt lgkmcnt(0)
	v_mfma_f32_32x32x16_bf16 v[96:111], v[134:137], v[138:141], v[96:111]
	ds_read_b128 v[138:141], v157 offset:17600
	ds_read_b128 v[142:145], v157 offset:192
	s_waitcnt lgkmcnt(0)
	v_mfma_f32_32x32x16_bf16 v[96:111], v[138:141], v[142:145], v[96:111]
	ds_read_b128 v[142:145], v157 offset:17632
	ds_read_b128 v[146:149], v157 offset:224
	s_waitcnt lgkmcnt(0)
	v_mfma_f32_32x32x16_bf16 v[96:111], v[142:145], v[146:149], v[96:111]
	s_nop 11
	v_cndmask_b32_e64 v146, v96, 0, s[34:35]
	v_cndmask_b32_e64 v96, v146, v96, s[30:31]
	v_cndmask_b32_e64 v97, 0, v97, s[30:31]
	v_cndmask_b32_e64 v98, v98, 0, s[28:29]
	v_cndmask_b32_e64 v99, v99, 0, s[26:27]
	v_cndmask_b32_e64 v100, v100, 0, s[24:25]
	v_cndmask_b32_e64 v101, v101, 0, s[22:23]
	v_cvt_pk_bf16_f32 v96, v96, v97
	v_cvt_pk_bf16_f32 v97, v98, v99
	v_cvt_pk_bf16_f32 v98, v100, v101
	v_add_u32_e32 v100, v171, v168
	v_add_u32_e32 v183, 0xd000, v100
	ds_read2_b64 v[146:149], v183 offset1:2
	ds_read2_b64 v[184:187], v183 offset0:4 offset1:6
	v_cndmask_b32_e64 v102, v102, 0, s[20:21]
	v_cndmask_b32_e64 v103, v103, 0, s[18:19]
	v_cvt_pk_bf16_f32 v99, v102, v103
	ds_read_b128 v[188:191], v157 offset:8704
	v_cndmask_b32_e64 v104, v104, 0, s[16:17]
	s_waitcnt lgkmcnt(2)
	v_mfma_f32_32x32x16_bf16 v[80:95], v[146:149], v[96:99], v[80:95]
	v_cndmask_b32_e64 v105, v105, 0, s[14:15]
	v_cndmask_b32_e64 v106, v106, 0, s[12:13]
	v_cndmask_b32_e64 v107, v107, 0, s[10:11]
	v_cndmask_b32_e64 v108, v108, 0, s[8:9]
	v_cndmask_b32_e64 v109, v109, 0, s[6:7]
	v_cndmask_b32_e64 v110, v110, 0, s[4:5]
	v_cndmask_b32_e64 v111, v111, 0, s[2:3]
	v_cvt_pk_bf16_f32 v96, v104, v105
	v_cvt_pk_bf16_f32 v97, v106, v107
	v_cvt_pk_bf16_f32 v98, v108, v109
	v_cvt_pk_bf16_f32 v99, v110, v111
	s_waitcnt lgkmcnt(1)
	s_nop 0
	v_mfma_f32_32x32x16_bf16 v[80:95], v[184:187], v[96:99], v[80:95]
	s_waitcnt lgkmcnt(0)
	v_mfma_f32_32x32x16_bf16 v[96:111], v[114:117], v[188:191], 0
	ds_read_b128 v[114:117], v157 offset:8736
	s_waitcnt lgkmcnt(0)
	v_mfma_f32_32x32x16_bf16 v[96:111], v[122:125], v[114:117], v[96:111]
	ds_read_b128 v[122:125], v157 offset:8768
	s_waitcnt lgkmcnt(0)
	v_mfma_f32_32x32x16_bf16 v[96:111], v[118:121], v[122:125], v[96:111]
	ds_read_b128 v[118:121], v157 offset:8800
	s_waitcnt lgkmcnt(0)
	v_mfma_f32_32x32x16_bf16 v[96:111], v[126:129], v[118:121], v[96:111]
	ds_read_b128 v[126:129], v157 offset:8832
	s_waitcnt lgkmcnt(0)
	v_mfma_f32_32x32x16_bf16 v[96:111], v[130:133], v[126:129], v[96:111]
	ds_read_b128 v[130:133], v157 offset:8864
	s_waitcnt lgkmcnt(0)
	v_mfma_f32_32x32x16_bf16 v[96:111], v[134:137], v[130:133], v[96:111]
	ds_read_b128 v[134:137], v157 offset:8896
	s_waitcnt lgkmcnt(0)
	v_mfma_f32_32x32x16_bf16 v[96:111], v[138:141], v[134:137], v[96:111]
	ds_read_b128 v[138:141], v157 offset:8928
	s_waitcnt lgkmcnt(0)
	v_mfma_f32_32x32x16_bf16 v[96:111], v[142:145], v[138:141], v[96:111]
	ds_read_b128 v[142:145], v157 offset:26144
	s_nop 10
	v_cvt_pk_bf16_f32 v96, v96, v97
	v_cvt_pk_bf16_f32 v97, v98, v99
	v_cvt_pk_bf16_f32 v98, v100, v101
	v_cvt_pk_bf16_f32 v99, v102, v103
	s_nop 1
	v_mfma_f32_32x32x16_bf16 v[64:79], v[146:149], v[96:99], v[64:79]
	v_cvt_pk_bf16_f32 v96, v104, v105
	v_cvt_pk_bf16_f32 v97, v106, v107
	v_cvt_pk_bf16_f32 v98, v108, v109
	v_cvt_pk_bf16_f32 v99, v110, v111
	s_nop 1
	v_mfma_f32_32x32x16_bf16 v[64:79], v[184:187], v[96:99], v[64:79]
	ds_read_b128 v[96:99], v157 offset:26112
	s_waitcnt lgkmcnt(0)
	v_mfma_f32_32x32x16_bf16 v[96:111], v[96:99], v[188:191], 0
	v_mfma_f32_32x32x16_bf16 v[96:111], v[142:145], v[114:117], v[96:111]
	ds_read_b128 v[114:117], v157 offset:26176
	s_waitcnt lgkmcnt(0)
	v_mfma_f32_32x32x16_bf16 v[96:111], v[114:117], v[122:125], v[96:111]
	ds_read_b128 v[114:117], v157 offset:26208
	s_waitcnt lgkmcnt(0)
	v_mfma_f32_32x32x16_bf16 v[96:111], v[114:117], v[118:121], v[96:111]
	ds_read_b128 v[114:117], v157 offset:26240
	s_waitcnt lgkmcnt(0)
	v_mfma_f32_32x32x16_bf16 v[96:111], v[114:117], v[126:129], v[96:111]
	ds_read_b128 v[114:117], v157 offset:26272
	s_waitcnt lgkmcnt(0)
	v_mfma_f32_32x32x16_bf16 v[96:111], v[114:117], v[130:133], v[96:111]
	ds_read_b128 v[114:117], v157 offset:26304
	s_waitcnt lgkmcnt(0)
	v_mfma_f32_32x32x16_bf16 v[96:111], v[114:117], v[134:137], v[96:111]
	ds_read_b128 v[114:117], v157 offset:26336
	v_ashrrev_i32_e32 v157, 31, v156
	s_waitcnt lgkmcnt(0)
	v_mfma_f32_32x32x16_bf16 v[96:111], v[114:117], v[138:141], v[96:111]
	s_nop 11
	v_cndmask_b32_e64 v114, v96, 0, s[34:35]
	v_cndmask_b32_e64 v96, v114, v96, s[30:31]
	v_cndmask_b32_e64 v97, 0, v97, s[30:31]
	v_cndmask_b32_e64 v98, v98, 0, s[28:29]
	v_cndmask_b32_e64 v99, v99, 0, s[26:27]
	v_cndmask_b32_e64 v100, v100, 0, s[24:25]
	v_cndmask_b32_e64 v101, v101, 0, s[22:23]
	v_cndmask_b32_e64 v102, v102, 0, s[20:21]
	v_cndmask_b32_e64 v103, v103, 0, s[18:19]
	v_cvt_pk_bf16_f32 v96, v96, v97
	v_cvt_pk_bf16_f32 v97, v98, v99
	v_cvt_pk_bf16_f32 v98, v100, v101
	v_cvt_pk_bf16_f32 v99, v102, v103
	ds_read2_b64 v[100:103], v183 offset0:8 offset1:10
	v_cndmask_b32_e64 v104, v104, 0, s[16:17]
	s_waitcnt lgkmcnt(0)
	v_mfma_f32_32x32x16_bf16 v[64:79], v[100:103], v[96:99], v[64:79]
	ds_read2_b64 v[100:103], v183 offset0:12 offset1:14
	v_cndmask_b32_e64 v105, v105, 0, s[14:15]
	v_cndmask_b32_e64 v106, v106, 0, s[12:13]
	v_cndmask_b32_e64 v107, v107, 0, s[10:11]
	v_cndmask_b32_e64 v108, v108, 0, s[8:9]
	v_cndmask_b32_e64 v109, v109, 0, s[6:7]
	v_cndmask_b32_e64 v110, v110, 0, s[4:5]
	v_cndmask_b32_e64 v111, v111, 0, s[2:3]
	v_cvt_pk_bf16_f32 v96, v104, v105
	v_cvt_pk_bf16_f32 v97, v106, v107
	v_cvt_pk_bf16_f32 v98, v108, v109
	v_cvt_pk_bf16_f32 v99, v110, v111
	v_add_u32_e32 v108, v171, v169
	s_waitcnt lgkmcnt(0)
	v_mfma_f32_32x32x16_bf16 v[64:79], v[100:103], v[96:99], v[64:79]
	ds_read_b128 v[96:99], v108 offset:53248
	ds_read_b128 v[100:103], v108 offset:53280
	ds_read_b128 v[104:107], v108 offset:53312
	ds_read_b128 v[108:111], v108 offset:53344
	ds_read_b128 v[114:117], v181 offset:34816
	ds_read_b128 v[118:121], v181 offset:34848
	s_waitcnt lgkmcnt(1)
	v_mfma_f32_32x32x16_bf16 v[48:63], v[114:117], v[96:99], v[48:63]
	ds_read_b128 v[114:117], v181 offset:34880
	s_waitcnt lgkmcnt(1)
	v_mfma_f32_32x32x16_bf16 v[48:63], v[118:121], v[100:103], v[48:63]
	s_waitcnt lgkmcnt(0)
	v_mfma_f32_32x32x16_bf16 v[48:63], v[114:117], v[104:107], v[48:63]
	ds_read_b128 v[114:117], v181 offset:34912
	s_waitcnt lgkmcnt(0)
	v_mfma_f32_32x32x16_bf16 v[48:63], v[114:117], v[108:111], v[48:63]
	ds_read_b128 v[114:117], v181 offset:39424
	s_waitcnt lgkmcnt(0)
	v_mfma_f32_32x32x16_bf16 v[32:47], v[114:117], v[96:99], v[32:47]
	ds_read_b128 v[114:117], v181 offset:39456
	s_waitcnt lgkmcnt(0)
	v_mfma_f32_32x32x16_bf16 v[32:47], v[114:117], v[100:103], v[32:47]
	ds_read_b128 v[114:117], v181 offset:39488
	s_waitcnt lgkmcnt(0)
	v_mfma_f32_32x32x16_bf16 v[32:47], v[114:117], v[104:107], v[32:47]
	ds_read_b128 v[114:117], v181 offset:39520
	s_waitcnt lgkmcnt(0)
	v_mfma_f32_32x32x16_bf16 v[32:47], v[114:117], v[108:111], v[32:47]
	ds_read_b128 v[114:117], v181 offset:44032
	s_waitcnt lgkmcnt(0)
	v_mfma_f32_32x32x16_bf16 v[16:31], v[114:117], v[96:99], v[16:31]
	ds_read_b128 v[114:117], v181 offset:44064
	s_waitcnt lgkmcnt(0)
	v_mfma_f32_32x32x16_bf16 v[16:31], v[114:117], v[100:103], v[16:31]
	ds_read_b128 v[114:117], v181 offset:44096
	s_waitcnt lgkmcnt(0)
	v_mfma_f32_32x32x16_bf16 v[16:31], v[114:117], v[104:107], v[16:31]
	ds_read_b128 v[114:117], v181 offset:44128
	s_waitcnt lgkmcnt(0)
	v_mfma_f32_32x32x16_bf16 v[16:31], v[114:117], v[108:111], v[16:31]
	ds_read_b128 v[114:117], v181 offset:48640
	s_waitcnt lgkmcnt(0)
	v_mfma_f32_32x32x16_bf16 v[0:15], v[114:117], v[96:99], v[0:15]
	ds_read_b128 v[96:99], v181 offset:48672
	s_waitcnt lgkmcnt(0)
	v_mfma_f32_32x32x16_bf16 v[0:15], v[96:99], v[100:103], v[0:15]
	ds_read_b128 v[96:99], v181 offset:48704
	s_waitcnt lgkmcnt(0)
	v_mfma_f32_32x32x16_bf16 v[0:15], v[96:99], v[104:107], v[0:15]
	ds_read_b128 v[96:99], v181 offset:48736
	s_waitcnt lgkmcnt(0)
	v_mfma_f32_32x32x16_bf16 v[0:15], v[96:99], v[108:111], v[0:15]
	ds_read_b128 v[96:99], v172
	ds_read_b128 v[100:103], v172 offset:32
	s_waitcnt lgkmcnt(1)
	v_mul_f32_e64 v108, v48, v96
	v_mul_f32_e64 v109, v49, v97
	v_pk_mul_f32 v[114:115], v[50:51], v[98:99]
	ds_read_b128 v[48:51], v172 offset:64
	s_waitcnt lgkmcnt(1)
	v_pk_mul_f32 v[52:53], v[52:53], v[100:101]
	v_pk_mul_f32 v[54:55], v[54:55], v[102:103]
	s_waitcnt lgkmcnt(0)
	v_pk_mul_f32 v[56:57], v[56:57], v[48:49]
	v_pk_mul_f32 v[58:59], v[58:59], v[50:51]
	ds_read_b128 v[48:51], v172 offset:96
	s_waitcnt lgkmcnt(0)
	v_pk_mul_f32 v[60:61], v[60:61], v[48:49]
	v_pk_mul_f32 v[62:63], v[62:63], v[50:51]
	ds_read_b128 v[48:51], v172 offset:128
	s_waitcnt lgkmcnt(0)
	v_pk_mul_f32 v[100:101], v[32:33], v[48:49]
	v_pk_mul_f32 v[96:97], v[34:35], v[50:51]
	ds_read_b128 v[32:35], v172 offset:160
	s_waitcnt lgkmcnt(0)
	v_pk_mul_f32 v[110:111], v[36:37], v[32:33]
	v_pk_mul_f32 v[102:103], v[38:39], v[34:35]
	ds_read_b128 v[32:35], v172 offset:192
	s_waitcnt lgkmcnt(0)
	v_pk_mul_f32 v[104:105], v[40:41], v[32:33]
	v_pk_mul_f32 v[98:99], v[42:43], v[34:35]
	ds_read_b128 v[32:35], v172 offset:224
	s_waitcnt lgkmcnt(0)
	v_pk_mul_f32 v[116:117], v[44:45], v[32:33]
	v_pk_mul_f32 v[106:107], v[46:47], v[34:35]
	ds_read_b128 v[32:35], v172 offset:256
	s_waitcnt lgkmcnt(0)
	v_pk_mul_f32 v[122:123], v[16:17], v[32:33]
	v_pk_mul_f32 v[118:119], v[18:19], v[34:35]
	ds_read_b128 v[16:19], v172 offset:288
	s_waitcnt lgkmcnt(0)
	v_pk_mul_f32 v[130:131], v[20:21], v[16:17]
	v_pk_mul_f32 v[124:125], v[22:23], v[18:19]
	ds_read_b128 v[16:19], v172 offset:320
	s_waitcnt lgkmcnt(0)
	v_pk_mul_f32 v[126:127], v[24:25], v[16:17]
	v_pk_mul_f32 v[120:121], v[26:27], v[18:19]
	ds_read_b128 v[16:19], v172 offset:352
	s_waitcnt lgkmcnt(0)
	v_pk_mul_f32 v[132:133], v[28:29], v[16:17]
	v_pk_mul_f32 v[128:129], v[30:31], v[18:19]
	ds_read_b128 v[16:19], v172 offset:384
	v_lshlrev_b64 v[30:31], 12, v[156:157]
	s_waitcnt lgkmcnt(0)
	v_pk_mul_f32 v[136:137], v[0:1], v[16:17]
	v_pk_mul_f32 v[134:135], v[2:3], v[18:19]
	ds_read_b128 v[0:3], v172 offset:416
	s_waitcnt lgkmcnt(0)
	v_pk_mul_f32 v[144:145], v[4:5], v[0:1]
	v_pk_mul_f32 v[138:139], v[6:7], v[2:3]
	ds_read_b128 v[0:3], v172 offset:448
	s_waitcnt lgkmcnt(0)
	v_pk_mul_f32 v[146:147], v[8:9], v[0:1]
	v_pk_mul_f32 v[140:141], v[10:11], v[2:3]
	ds_read_b128 v[0:3], v172 offset:480
	s_waitcnt lgkmcnt(0)
	s_barrier
	ds_write_b128 v182, v[80:83]
	ds_write_b128 v182, v[84:87] offset:32
	ds_write_b128 v182, v[88:91] offset:64
	ds_write_b128 v182, v[92:95] offset:96
	ds_write_b128 v182, v[64:67] offset:16896
	ds_write_b128 v182, v[68:71] offset:16928
	ds_write_b128 v182, v[72:75] offset:16960
	ds_write_b128 v182, v[76:79] offset:16992
	v_pk_mul_f32 v[148:149], v[12:13], v[0:1]
	v_pk_mul_f32 v[142:143], v[14:15], v[2:3]
	s_waitcnt lgkmcnt(0)
	s_barrier
	ds_read_b128 v[16:19], v173 offset:64
	ds_read_b128 v[12:15], v173 offset:80
	v_lshl_add_u64 v[64:65], v[152:153], 0, v[30:31]
	s_waitcnt lgkmcnt(1)
	v_pk_mul_f32 v[4:5], v[16:17], v[16:17]
	s_waitcnt lgkmcnt(0)
	v_pk_mul_f32 v[6:7], v[12:13], v[12:13]
	v_pk_mul_f32 v[0:1], v[18:19], v[18:19]
	v_pk_mul_f32 v[2:3], v[14:15], v[14:15]
	v_mov_b32_e32 v8, v4
	v_mov_b32_e32 v9, v6
	v_mov_b32_e32 v6, v5
	v_pk_add_f32 v[4:5], v[8:9], v[6:7]
	v_mov_b32_e32 v6, v0
	v_mov_b32_e32 v7, v2
	v_pk_add_f32 v[4:5], v[4:5], v[6:7]
	v_mov_b32_e32 v2, v1
	v_pk_add_f32 v[66:67], v[4:5], v[2:3]
	ds_read_b128 v[4:7], v173 offset:96
	ds_read_b128 v[0:3], v173 offset:112
	s_waitcnt lgkmcnt(1)
	v_pk_mul_f32 v[20:21], v[4:5], v[4:5]
	s_waitcnt lgkmcnt(0)
	v_pk_mul_f32 v[22:23], v[0:1], v[0:1]
	v_pk_mul_f32 v[8:9], v[6:7], v[6:7]
	v_pk_mul_f32 v[10:11], v[2:3], v[2:3]
	v_mov_b32_e32 v24, v20
	v_mov_b32_e32 v25, v22
	v_mov_b32_e32 v22, v21
	v_pk_add_f32 v[20:21], v[24:25], v[22:23]
	v_mov_b32_e32 v22, v8
	v_mov_b32_e32 v23, v10
	v_mov_b32_e32 v10, v9
	v_lshl_add_u64 v[8:9], v[156:157], 0, s[46:47]
	v_lshlrev_b64 v[8:9], 8, v[8:9]
	v_pk_add_f32 v[20:21], v[20:21], v[22:23]
	v_lshl_add_u64 v[28:29], v[150:151], 0, v[8:9]
	v_pk_add_f32 v[68:69], v[20:21], v[10:11]
	ds_read_b128 v[48:51], v173
	ds_read_b128 v[40:43], v173 offset:16
	ds_read_b128 v[32:35], v173 offset:32
	ds_read_b128 v[28:31], v173 offset:48
	global_load_dwordx4 v[36:39], v[154:155], off offset:16
	global_load_dwordx4 v[44:47], v[154:155], off
	s_waitcnt lgkmcnt(3)
	v_mov_b32_e32 v84, v49
	s_waitcnt lgkmcnt(2)
	v_mov_b32_e32 v85, v41
	v_mov_b32_e32 v78, v48
	v_mov_b32_e32 v79, v40
	v_pk_mul_f32 v[84:85], v[84:85], v[84:85]
	s_waitcnt lgkmcnt(1)
	v_mov_b32_e32 v90, v33
	v_pk_fma_f32 v[78:79], v[78:79], v[78:79], v[84:85]
	s_waitcnt lgkmcnt(0)
	v_mov_b32_e32 v91, v29
	v_mov_b32_e32 v74, v51
	v_mov_b32_e32 v75, v43
	v_mov_b32_e32 v88, v32
	v_mov_b32_e32 v89, v28
	v_pk_mul_f32 v[90:91], v[90:91], v[90:91]
	v_mov_b32_e32 v86, v35
	v_pk_fma_f32 v[88:89], v[88:89], v[88:89], v[90:91]
	v_mov_b32_e32 v87, v31
	v_add_u32_e32 v156, 64, v156
	s_waitcnt vmcnt(2)
	v_lshlrev_b32_e32 v80, 16, v229
	v_and_b32_e32 v81, 0xffff0000, v229
	v_lshlrev_b32_e32 v82, 16, v228
	v_and_b32_e32 v83, 0xffff0000, v228
	v_mov_b32_e32 v70, v50
	v_mov_b32_e32 v71, v42
	v_pk_fma_f32 v[70:71], v[70:71], v[70:71], v[78:79]
	v_lshlrev_b32_e32 v76, 16, v230
	v_and_b32_e32 v77, 0xffff0000, v230
	v_pk_fma_f32 v[84:85], v[74:75], v[74:75], v[70:71]
	v_lshlrev_b32_e32 v78, 16, v231
	v_and_b32_e32 v79, 0xffff0000, v231
	v_lshlrev_b32_e32 v72, 16, v225
	v_and_b32_e32 v73, 0xffff0000, v225
	v_lshlrev_b32_e32 v74, 16, v224
	v_and_b32_e32 v75, 0xffff0000, v224
	v_mov_b32_e32 v24, v34
	v_mov_b32_e32 v25, v30
	v_pk_fma_f32 v[24:25], v[24:25], v[24:25], v[88:89]
	v_lshlrev_b32_e32 v70, 16, v226
	v_and_b32_e32 v71, 0xffff0000, v226
	v_pk_fma_f32 v[24:25], v[86:87], v[86:87], v[24:25]
	v_add_f32_e32 v26, v84, v85
	v_add_f32_e32 v24, v26, v24
	v_add_f32_e32 v24, v24, v25
	v_add_f32_e32 v24, v24, v66
	v_add_f32_e32 v24, v24, v67
	v_add_f32_e32 v24, v24, v68
	v_add_f32_e32 v24, v24, v69
	ds_bpermute_b32 v25, v174, v24
	v_lshlrev_b32_e32 v26, 16, v227
	v_and_b32_e32 v27, 0xffff0000, v227
	s_waitcnt lgkmcnt(0)
	v_add_f32_e32 v24, v24, v25
	ds_bpermute_b32 v25, v175, v24
	s_waitcnt lgkmcnt(0)
	v_add_f32_e32 v24, v24, v25
	v_fmamk_f32 v24, v24, 0x3c000000, v161
	v_cmp_gt_f32_e64 s[36:37], s70, v24
	v_mul_f32_e32 v25, 0x4b800000, v24
	s_nop 0
	v_cndmask_b32_e64 v24, v24, v25, s[36:37]
	v_rsq_f32_e32 v24, v24
	s_nop 0
	v_mul_f32_e32 v25, 0x45800000, v24
	v_cndmask_b32_e64 v24, v24, v25, s[36:37]
	v_pk_mul_f32 v[48:49], v[48:49], v[24:25] op_sel_hi:[1,0]
	v_pk_mul_f32 v[40:41], v[40:41], v[24:25] op_sel_hi:[1,0]
	s_waitcnt vmcnt(0)
	v_pk_mul_f32 v[44:45], v[44:45], v[48:49]
	v_pk_mul_f32 v[48:49], v[50:51], v[24:25] op_sel_hi:[1,0]
	v_pk_mul_f32 v[36:37], v[36:37], v[40:41]
	v_pk_mul_f32 v[46:47], v[46:47], v[48:49]
	v_pk_mul_f32 v[44:45], v[44:45], v[82:83]
	v_pk_mul_f32 v[46:47], v[46:47], v[80:81]
	v_pk_mul_f32 v[36:37], v[36:37], v[76:77]
	v_cvt_pk_bf16_f32 v44, v44, v45
	v_cvt_pk_bf16_f32 v45, v46, v47
	v_cvt_pk_bf16_f32 v46, v36, v37
	v_pk_mul_f32 v[36:37], v[42:43], v[24:25] op_sel_hi:[1,0]
	v_pk_mul_f32 v[32:33], v[32:33], v[24:25] op_sel_hi:[1,0]
	v_pk_mul_f32 v[36:37], v[36:37], v[38:39]
	v_pk_mul_f32 v[34:35], v[34:35], v[24:25] op_sel_hi:[1,0]
	v_pk_mul_f32 v[36:37], v[36:37], v[78:79]
	v_pk_mul_f32 v[28:29], v[28:29], v[24:25] op_sel_hi:[1,0]
	v_cvt_pk_bf16_f32 v47, v36, v37
	global_store_dwordx4 v[64:65], v[44:47], off
	global_load_dwordx4 v[36:39], v[154:155], off offset:48
	global_load_dwordx4 v[40:43], v[154:155], off offset:32
	v_pk_mul_f32 v[16:17], v[16:17], v[24:25] op_sel_hi:[1,0]
	v_pk_mul_f32 v[18:19], v[18:19], v[24:25] op_sel_hi:[1,0]
	v_pk_mul_f32 v[12:13], v[12:13], v[24:25] op_sel_hi:[1,0]
	v_pk_mul_f32 v[4:5], v[4:5], v[24:25] op_sel_hi:[1,0]
	v_pk_mul_f32 v[6:7], v[6:7], v[24:25] op_sel_hi:[1,0]
	v_pk_mul_f32 v[0:1], v[0:1], v[24:25] op_sel_hi:[1,0]
	s_waitcnt vmcnt(1)
	v_pk_mul_f32 v[28:29], v[28:29], v[36:37]
	s_waitcnt vmcnt(0)
	v_pk_mul_f32 v[32:33], v[32:33], v[40:41]
	v_pk_mul_f32 v[34:35], v[34:35], v[42:43]
	v_pk_mul_f32 v[32:33], v[32:33], v[74:75]
	v_pk_mul_f32 v[34:35], v[34:35], v[72:73]
	v_pk_mul_f32 v[28:29], v[28:29], v[70:71]
	v_cvt_pk_bf16_f32 v32, v32, v33
	v_cvt_pk_bf16_f32 v33, v34, v35
	v_cvt_pk_bf16_f32 v34, v28, v29
	v_pk_mul_f32 v[28:29], v[30:31], v[24:25] op_sel_hi:[1,0]
	s_nop 0
	v_pk_mul_f32 v[28:29], v[28:29], v[38:39]
	s_nop 0
	v_pk_mul_f32 v[26:27], v[28:29], v[26:27]
	s_nop 0
	v_cvt_pk_bf16_f32 v35, v26, v27
	global_store_dwordx4 v[64:65], v[32:35], off offset:16
	global_load_dwordx4 v[26:29], v[154:155], off offset:80
	s_nop 0
	global_load_dwordx4 v[30:33], v[154:155], off offset:64
	s_waitcnt vmcnt(1)
	v_pk_mul_f32 v[12:13], v[12:13], v[26:27]
	s_waitcnt vmcnt(0)
	v_pk_mul_f32 v[16:17], v[16:17], v[30:31]
	v_lshlrev_b32_e32 v30, 16, v220
	v_and_b32_e32 v31, 0xffff0000, v220
	v_pk_mul_f32 v[18:19], v[18:19], v[32:33]
	v_lshlrev_b32_e32 v20, 16, v221
	v_and_b32_e32 v21, 0xffff0000, v221
	v_pk_mul_f32 v[16:17], v[16:17], v[30:31]
	v_pk_mul_f32 v[18:19], v[18:19], v[20:21]
	v_cvt_pk_bf16_f32 v16, v16, v17
	v_cvt_pk_bf16_f32 v17, v18, v19
	v_lshlrev_b32_e32 v18, 16, v222
	v_and_b32_e32 v19, 0xffff0000, v222
	v_pk_mul_f32 v[12:13], v[12:13], v[18:19]
	s_nop 0
	v_cvt_pk_bf16_f32 v18, v12, v13
	v_pk_mul_f32 v[12:13], v[14:15], v[24:25] op_sel_hi:[1,0]
	v_lshlrev_b32_e32 v14, 16, v223
	v_pk_mul_f32 v[12:13], v[12:13], v[28:29]
	v_and_b32_e32 v15, 0xffff0000, v223
	v_pk_mul_f32 v[12:13], v[12:13], v[14:15]
	s_nop 0
	v_cvt_pk_bf16_f32 v19, v12, v13
	global_store_dwordx4 v[64:65], v[16:19], off offset:32
	global_load_dwordx4 v[12:15], v[154:155], off offset:112
	s_nop 0
	global_load_dwordx4 v[16:19], v[154:155], off offset:96
	s_waitcnt vmcnt(1)
	v_pk_mul_f32 v[0:1], v[0:1], v[12:13]
	s_waitcnt vmcnt(0)
	v_pk_mul_f32 v[4:5], v[4:5], v[16:17]
	v_lshlrev_b32_e32 v16, 16, v216
	v_and_b32_e32 v17, 0xffff0000, v216
	v_pk_mul_f32 v[6:7], v[6:7], v[18:19]
	v_lshlrev_b32_e32 v8, 16, v217
	v_and_b32_e32 v9, 0xffff0000, v217
	v_pk_mul_f32 v[4:5], v[4:5], v[16:17]
	v_pk_mul_f32 v[6:7], v[6:7], v[8:9]
	v_cvt_pk_bf16_f32 v4, v4, v5
	v_cvt_pk_bf16_f32 v5, v6, v7
	v_lshlrev_b32_e32 v6, 16, v218
	v_and_b32_e32 v7, 0xffff0000, v218
	v_pk_mul_f32 v[0:1], v[0:1], v[6:7]
	s_nop 0
	v_cvt_pk_bf16_f32 v6, v0, v1
	v_pk_mul_f32 v[0:1], v[2:3], v[24:25] op_sel_hi:[1,0]
	v_lshlrev_b32_e32 v2, 16, v219
	v_pk_mul_f32 v[0:1], v[0:1], v[14:15]
	v_and_b32_e32 v3, 0xffff0000, v219
	v_pk_mul_f32 v[0:1], v[0:1], v[2:3]
	s_nop 0
	v_cvt_pk_bf16_f32 v7, v0, v1
	global_store_dwordx4 v[64:65], v[4:7], off offset:48
	s_cbranch_scc1 .LBB0_425
